# remove the compiler's per-unit s_waitcnt vmcnt(0) drain at the GEMM unit heads (the K-loop's counted waits cover the prefetched tiles)
# baseline (speedup 1.0000x reference)
.LBB0_231:
	s_ashr_i32 s77, s76, 31
	s_lshl_b64 s[66:67], s[76:77], 19
	s_add_u32 s80, s12, s66
	s_addc_u32 s81, s13, s67
	s_and_b64 s[66:67], s[78:79], exec
	s_cselect_b32 s66, s81, s85
	s_cselect_b32 s67, s80, s84
	s_ashr_i32 s75, s74, 31
	s_lshl_b64 s[68:69], s[74:75], 19
	s_add_u32 s82, s5, s68
	s_addc_u32 s83, s20, s69
	s_and_b64 s[68:69], s[78:79], exec
	s_cselect_b32 s68, s83, s87
	s_cselect_b32 s69, s82, s86
	s_add_u32 s84, s84, 0x40080
	s_addc_u32 s85, s85, 0
	s_add_u32 s75, s86, 0x100
	v_mov_b64_e32 v[0:1], 0
	s_addc_u32 s77, s87, 0
	s_mov_b32 s90, -2
	v_mov_b64_e32 v[2:3], 0
	v_mov_b64_e32 v[4:5], 0
	v_mov_b64_e32 v[6:7], 0
	v_mov_b64_e32 v[8:9], 0
	v_mov_b64_e32 v[10:11], 0
	v_mov_b64_e32 v[12:13], 0
	v_mov_b64_e32 v[14:15], 0
	v_mov_b64_e32 v[16:17], 0
	v_mov_b64_e32 v[18:19], 0
	v_mov_b64_e32 v[20:21], 0
	v_mov_b64_e32 v[22:23], 0
	v_mov_b64_e32 v[24:25], 0
	v_mov_b64_e32 v[26:27], 0
	v_mov_b64_e32 v[28:29], 0
	v_mov_b64_e32 v[30:31], 0
	v_mov_b64_e32 v[32:33], 0
	v_mov_b64_e32 v[34:35], 0
	v_mov_b64_e32 v[36:37], 0
	v_mov_b64_e32 v[38:39], 0
	v_mov_b64_e32 v[40:41], 0
	v_mov_b64_e32 v[42:43], 0
	v_mov_b64_e32 v[44:45], 0
	v_mov_b64_e32 v[46:47], 0
	v_mov_b64_e32 v[48:49], 0
	v_mov_b64_e32 v[50:51], 0
	v_mov_b64_e32 v[52:53], 0
	v_mov_b64_e32 v[54:55], 0
	v_mov_b64_e32 v[56:57], 0
	v_mov_b64_e32 v[58:59], 0
	v_mov_b64_e32 v[60:61], 0
	v_mov_b64_e32 v[62:63], 0
	v_mov_b64_e32 v[64:65], 0
	v_mov_b64_e32 v[66:67], 0
	v_mov_b64_e32 v[68:69], 0
	v_mov_b64_e32 v[70:71], 0
	v_mov_b64_e32 v[72:73], 0
	v_mov_b64_e32 v[74:75], 0
	v_mov_b64_e32 v[76:77], 0
	v_mov_b64_e32 v[78:79], 0
	v_mov_b64_e32 v[80:81], 0
	v_mov_b64_e32 v[82:83], 0
	v_mov_b64_e32 v[84:85], 0
	v_mov_b64_e32 v[86:87], 0
	v_mov_b64_e32 v[88:89], 0
	v_mov_b64_e32 v[90:91], 0
	v_mov_b64_e32 v[92:93], 0
	v_mov_b64_e32 v[94:95], 0
	v_mov_b64_e32 v[100:101], 0
	v_mov_b64_e32 v[102:103], 0
	v_mov_b64_e32 v[104:105], 0
	v_mov_b64_e32 v[106:107], 0
	v_mov_b64_e32 v[108:109], 0
	v_mov_b64_e32 v[110:111], 0
	v_mov_b64_e32 v[112:113], 0
	v_mov_b64_e32 v[114:115], 0
	v_mov_b64_e32 v[116:117], 0
	v_mov_b64_e32 v[118:119], 0
	v_mov_b64_e32 v[120:121], 0
	v_mov_b64_e32 v[122:123], 0
	v_mov_b64_e32 v[124:125], 0
	v_mov_b64_e32 v[126:127], 0
	v_mov_b64_e32 v[128:129], 0
	v_mov_b64_e32 v[130:131], 0
.LBB0_232:
	s_add_u32 s0, s84, 0xfffc0080
	s_addc_u32 s86, s85, -1
	s_add_i32 s96, 0, 0x10000
	s_cmp_eq_u32 s90, 12
	s_cselect_b32 s89, s66, s86
	s_cselect_b32 s88, s67, s0
	s_cselect_b32 s87, s68, s77
	s_cselect_b32 s86, s69, s75
	s_add_i32 s0, 0, 0x14000
	v_add_u32_e32 v160, s96, v145
	v_add_u32_e32 v176, s0, v145
	ds_read_b128 v[140:143], v160
	ds_read_b128 v[152:155], v160 offset:1024
	ds_read_b128 v[156:159], v160 offset:2048
	ds_read_b128 v[160:163], v160 offset:3072
	ds_read_b128 v[164:167], v176
	ds_read_b128 v[168:171], v176 offset:1024
	ds_read_b128 v[172:175], v176 offset:2048
	ds_read_b128 v[176:179], v176 offset:3072
	v_lshl_add_u64 v[180:181], s[84:85], 0, v[136:137]
	s_add_i32 m0, s22, 0xc000
	ds_read_b128 v[188:191], v151
	ds_read_b128 v[220:223], v151 offset:1024
	ds_read_b128 v[224:227], v151 offset:2048
	ds_read_b128 v[228:231], v151 offset:3072
	ds_read_b128 v[232:235], v151 offset:4096
	ds_read_b128 v[236:239], v151 offset:5120
	ds_read_b128 v[240:243], v151 offset:6144
	ds_read_b128 v[244:247], v151 offset:7168
	global_load_lds_dwordx4 v[180:181], off
	v_lshl_add_u64 v[180:181], s[84:85], 0, v[138:139]
	s_add_i32 m0, s22, 0xe000
	s_nop 0
	global_load_lds_dwordx4 v[180:181], off
	s_waitcnt vmcnt(8)
	s_waitcnt lgkmcnt(0)
	s_barrier
	s_setprio 1
	s_waitcnt lgkmcnt(0)
	v_mfma_f32_16x16x32_bf16 v[128:131], v[140:143], v[188:191], v[128:131]
	v_mfma_f32_16x16x32_bf16 v[124:127], v[156:159], v[188:191], v[124:127]
	v_mfma_f32_16x16x32_bf16 v[112:115], v[140:143], v[224:227], v[112:115]
	v_mfma_f32_16x16x32_bf16 v[108:111], v[156:159], v[224:227], v[108:111]
	v_mfma_f32_16x16x32_bf16 v[92:95], v[140:143], v[232:235], v[92:95]
	v_mfma_f32_16x16x32_bf16 v[88:91], v[156:159], v[232:235], v[88:91]
	v_mfma_f32_16x16x32_bf16 v[76:79], v[140:143], v[240:243], v[76:79]
	v_mfma_f32_16x16x32_bf16 v[72:75], v[156:159], v[240:243], v[72:75]
	v_mfma_f32_16x16x32_bf16 v[128:131], v[152:155], v[220:223], v[128:131]
	v_mfma_f32_16x16x32_bf16 v[124:127], v[160:163], v[220:223], v[124:127]
	v_mfma_f32_16x16x32_bf16 v[112:115], v[152:155], v[228:231], v[112:115]
	v_mfma_f32_16x16x32_bf16 v[108:111], v[160:163], v[228:231], v[108:111]
	v_mfma_f32_16x16x32_bf16 v[92:95], v[152:155], v[236:239], v[92:95]
	v_mfma_f32_16x16x32_bf16 v[88:91], v[160:163], v[236:239], v[88:91]
	v_mfma_f32_16x16x32_bf16 v[76:79], v[152:155], v[244:247], v[76:79]
	v_mfma_f32_16x16x32_bf16 v[72:75], v[160:163], v[244:247], v[72:75]
	s_setprio 0
	s_setprio 1
	v_mfma_f32_16x16x32_bf16 v[120:123], v[164:167], v[188:191], v[120:123]
	v_mfma_f32_16x16x32_bf16 v[116:119], v[172:175], v[188:191], v[116:119]
	v_mfma_f32_16x16x32_bf16 v[104:107], v[164:167], v[224:227], v[104:107]
	v_mfma_f32_16x16x32_bf16 v[100:103], v[172:175], v[224:227], v[100:103]
	v_mfma_f32_16x16x32_bf16 v[84:87], v[164:167], v[232:235], v[84:87]
	v_mfma_f32_16x16x32_bf16 v[80:83], v[172:175], v[232:235], v[80:83]
	v_mfma_f32_16x16x32_bf16 v[68:71], v[164:167], v[240:243], v[68:71]
	v_mfma_f32_16x16x32_bf16 v[64:67], v[172:175], v[240:243], v[64:67]
	v_mfma_f32_16x16x32_bf16 v[120:123], v[168:171], v[220:223], v[120:123]
	v_mfma_f32_16x16x32_bf16 v[116:119], v[176:179], v[220:223], v[116:119]
	v_mfma_f32_16x16x32_bf16 v[104:107], v[168:171], v[228:231], v[104:107]
	v_mfma_f32_16x16x32_bf16 v[100:103], v[176:179], v[228:231], v[100:103]
	v_mfma_f32_16x16x32_bf16 v[84:87], v[168:171], v[236:239], v[84:87]
	v_mfma_f32_16x16x32_bf16 v[80:83], v[176:179], v[236:239], v[80:83]
	v_mfma_f32_16x16x32_bf16 v[68:71], v[168:171], v[244:247], v[68:71]
	v_mfma_f32_16x16x32_bf16 v[64:67], v[176:179], v[244:247], v[64:67]
	s_setprio 0
	s_barrier
	s_add_i32 s96, s96, s1
	v_lshl_add_u64 v[180:181], s[86:87], 0, v[98:99]
	s_mov_b32 m0, s96
	ds_read_b128 v[188:191], v151 offset:16384
	ds_read_b128 v[220:223], v151 offset:17408
	ds_read_b128 v[224:227], v151 offset:18432
	ds_read_b128 v[228:231], v151 offset:19456
	ds_read_b128 v[232:235], v151 offset:20480
	ds_read_b128 v[236:239], v151 offset:21504
	ds_read_b128 v[240:243], v151 offset:22528
	ds_read_b128 v[244:247], v151 offset:23552
	global_load_lds_dwordx4 v[180:181], off
	s_add_i32 m0, s96, 0x2000
	s_add_u32 s96, s86, 0x40000
	v_lshl_add_u64 v[192:193], s[86:87], 0, v[134:135]
	s_addc_u32 s97, s87, 0
	s_add_i32 s0, s0, s1
	global_load_lds_dwordx4 v[192:193], off
	v_lshl_add_u64 v[248:249], s[96:97], 0, v[98:99]
	s_mov_b32 m0, s0
	v_lshl_add_u64 v[250:251], s[88:89], 0, v[132:133]
	global_load_lds_dwordx4 v[248:249], off
	v_lshl_add_u64 v[248:249], s[96:97], 0, v[134:135]
	s_add_i32 m0, s0, 0x2000
	s_nop 0
	global_load_lds_dwordx4 v[248:249], off
	v_lshl_add_u64 v[248:249], s[88:89], 0, v[96:97]
	s_mov_b32 m0, s22
	s_nop 0
	global_load_lds_dwordx4 v[248:249], off
	s_mov_b32 m0, s23
	s_nop 0
	global_load_lds_dwordx4 v[250:251], off
	s_waitcnt vmcnt(8)
	s_waitcnt lgkmcnt(0)
	s_barrier
	s_setprio 1
	s_waitcnt lgkmcnt(0)
	v_mfma_f32_16x16x32_bf16 v[60:63], v[140:143], v[188:191], v[60:63]
	v_mfma_f32_16x16x32_bf16 v[56:59], v[156:159], v[188:191], v[56:59]
	v_mfma_f32_16x16x32_bf16 v[44:47], v[140:143], v[224:227], v[44:47]
	v_mfma_f32_16x16x32_bf16 v[40:43], v[156:159], v[224:227], v[40:43]
	v_mfma_f32_16x16x32_bf16 v[28:31], v[140:143], v[232:235], v[28:31]
	v_mfma_f32_16x16x32_bf16 v[24:27], v[156:159], v[232:235], v[24:27]
	v_mfma_f32_16x16x32_bf16 v[12:15], v[140:143], v[240:243], v[12:15]
	v_mfma_f32_16x16x32_bf16 v[8:11], v[156:159], v[240:243], v[8:11]
	v_mfma_f32_16x16x32_bf16 v[60:63], v[152:155], v[220:223], v[60:63]
	v_mfma_f32_16x16x32_bf16 v[56:59], v[160:163], v[220:223], v[56:59]
	v_mfma_f32_16x16x32_bf16 v[44:47], v[152:155], v[228:231], v[44:47]
	v_mfma_f32_16x16x32_bf16 v[40:43], v[160:163], v[228:231], v[40:43]
	v_mfma_f32_16x16x32_bf16 v[28:31], v[152:155], v[236:239], v[28:31]
	v_mfma_f32_16x16x32_bf16 v[24:27], v[160:163], v[236:239], v[24:27]
	v_mfma_f32_16x16x32_bf16 v[12:15], v[152:155], v[244:247], v[12:15]
	v_mfma_f32_16x16x32_bf16 v[8:11], v[160:163], v[244:247], v[8:11]
	s_setprio 0
	s_setprio 1
	v_mfma_f32_16x16x32_bf16 v[52:55], v[164:167], v[188:191], v[52:55]
	v_mfma_f32_16x16x32_bf16 v[48:51], v[172:175], v[188:191], v[48:51]
	v_mfma_f32_16x16x32_bf16 v[36:39], v[164:167], v[224:227], v[36:39]
	v_mfma_f32_16x16x32_bf16 v[32:35], v[172:175], v[224:227], v[32:35]
	v_mfma_f32_16x16x32_bf16 v[20:23], v[164:167], v[232:235], v[20:23]
	v_mfma_f32_16x16x32_bf16 v[16:19], v[172:175], v[232:235], v[16:19]
	v_mfma_f32_16x16x32_bf16 v[4:7], v[164:167], v[240:243], v[4:7]
	v_mfma_f32_16x16x32_bf16 v[0:3], v[172:175], v[240:243], v[0:3]
	v_mfma_f32_16x16x32_bf16 v[52:55], v[168:171], v[220:223], v[52:55]
	v_mfma_f32_16x16x32_bf16 v[48:51], v[176:179], v[220:223], v[48:51]
	v_mfma_f32_16x16x32_bf16 v[36:39], v[168:171], v[228:231], v[36:39]
	v_mfma_f32_16x16x32_bf16 v[32:35], v[176:179], v[228:231], v[32:35]
	v_mfma_f32_16x16x32_bf16 v[20:23], v[168:171], v[236:239], v[20:23]
	v_mfma_f32_16x16x32_bf16 v[16:19], v[176:179], v[236:239], v[16:19]
	v_mfma_f32_16x16x32_bf16 v[4:7], v[168:171], v[244:247], v[4:7]
	v_mfma_f32_16x16x32_bf16 v[0:3], v[176:179], v[244:247], v[0:3]
	s_setprio 0
	s_barrier
	s_add_i32 s0, 0, 0x18000
	s_add_i32 s96, 0, 0x1c000
	v_add_u32_e32 v160, s0, v145
	v_add_u32_e32 v176, s96, v145
	ds_read_b128 v[140:143], v160
	ds_read_b128 v[152:155], v160 offset:1024
	ds_read_b128 v[156:159], v160 offset:2048
	ds_read_b128 v[160:163], v160 offset:3072
	ds_read_b128 v[164:167], v176
	ds_read_b128 v[168:171], v176 offset:1024
	ds_read_b128 v[172:175], v176 offset:2048
	ds_read_b128 v[176:179], v176 offset:3072
	s_add_u32 s88, s88, 0x40000
	s_addc_u32 s89, s89, 0
	s_mov_b32 m0, s26
	v_lshl_add_u64 v[252:253], s[88:89], 0, v[96:97]
	ds_read_b128 v[188:191], v151 offset:32768
	ds_read_b128 v[220:223], v151 offset:33792
	ds_read_b128 v[224:227], v151 offset:34816
	ds_read_b128 v[228:231], v151 offset:35840
	ds_read_b128 v[232:235], v151 offset:36864
	ds_read_b128 v[236:239], v151 offset:37888
	ds_read_b128 v[240:243], v151 offset:38912
	ds_read_b128 v[244:247], v151 offset:39936
	global_load_lds_dwordx4 v[252:253], off
	v_lshl_add_u64 v[252:253], s[88:89], 0, v[132:133]
	s_mov_b32 m0, s27
	s_nop 0
	global_load_lds_dwordx4 v[252:253], off
	s_waitcnt vmcnt(8)
	s_waitcnt lgkmcnt(0)
	s_barrier
	s_setprio 1
	s_waitcnt lgkmcnt(0)
	v_mfma_f32_16x16x32_bf16 v[128:131], v[140:143], v[188:191], v[128:131]
	v_mfma_f32_16x16x32_bf16 v[124:127], v[156:159], v[188:191], v[124:127]
	v_mfma_f32_16x16x32_bf16 v[112:115], v[140:143], v[224:227], v[112:115]
	v_mfma_f32_16x16x32_bf16 v[108:111], v[156:159], v[224:227], v[108:111]
	v_mfma_f32_16x16x32_bf16 v[92:95], v[140:143], v[232:235], v[92:95]
	v_mfma_f32_16x16x32_bf16 v[88:91], v[156:159], v[232:235], v[88:91]
	v_mfma_f32_16x16x32_bf16 v[76:79], v[140:143], v[240:243], v[76:79]
	v_mfma_f32_16x16x32_bf16 v[72:75], v[156:159], v[240:243], v[72:75]
	v_mfma_f32_16x16x32_bf16 v[128:131], v[152:155], v[220:223], v[128:131]
	v_mfma_f32_16x16x32_bf16 v[124:127], v[160:163], v[220:223], v[124:127]
	v_mfma_f32_16x16x32_bf16 v[112:115], v[152:155], v[228:231], v[112:115]
	v_mfma_f32_16x16x32_bf16 v[108:111], v[160:163], v[228:231], v[108:111]
	v_mfma_f32_16x16x32_bf16 v[92:95], v[152:155], v[236:239], v[92:95]
	v_mfma_f32_16x16x32_bf16 v[88:91], v[160:163], v[236:239], v[88:91]
	v_mfma_f32_16x16x32_bf16 v[76:79], v[152:155], v[244:247], v[76:79]
	v_mfma_f32_16x16x32_bf16 v[72:75], v[160:163], v[244:247], v[72:75]
	s_setprio 0
	s_setprio 1
	v_mfma_f32_16x16x32_bf16 v[120:123], v[164:167], v[188:191], v[120:123]
	v_mfma_f32_16x16x32_bf16 v[116:119], v[172:175], v[188:191], v[116:119]
	v_mfma_f32_16x16x32_bf16 v[104:107], v[164:167], v[224:227], v[104:107]
	v_mfma_f32_16x16x32_bf16 v[100:103], v[172:175], v[224:227], v[100:103]
	v_mfma_f32_16x16x32_bf16 v[84:87], v[164:167], v[232:235], v[84:87]
	v_mfma_f32_16x16x32_bf16 v[80:83], v[172:175], v[232:235], v[80:83]
	v_mfma_f32_16x16x32_bf16 v[68:71], v[164:167], v[240:243], v[68:71]
	v_mfma_f32_16x16x32_bf16 v[64:67], v[172:175], v[240:243], v[64:67]
	v_mfma_f32_16x16x32_bf16 v[120:123], v[168:171], v[220:223], v[120:123]
	v_mfma_f32_16x16x32_bf16 v[116:119], v[176:179], v[220:223], v[116:119]
	v_mfma_f32_16x16x32_bf16 v[104:107], v[168:171], v[228:231], v[104:107]
	v_mfma_f32_16x16x32_bf16 v[100:103], v[176:179], v[228:231], v[100:103]
	v_mfma_f32_16x16x32_bf16 v[84:87], v[168:171], v[236:239], v[84:87]
	v_mfma_f32_16x16x32_bf16 v[80:83], v[176:179], v[236:239], v[80:83]
	v_mfma_f32_16x16x32_bf16 v[68:71], v[168:171], v[244:247], v[68:71]
	v_mfma_f32_16x16x32_bf16 v[64:67], v[176:179], v[244:247], v[64:67]
	s_setprio 0
	s_barrier
	s_add_i32 s0, s0, s1
	v_lshl_add_u64 v[180:181], v[180:181], 0, s[58:59]
	s_mov_b32 m0, s0
	ds_read_b128 v[188:191], v151 offset:49152
	ds_read_b128 v[220:223], v151 offset:50176
	ds_read_b128 v[224:227], v151 offset:51200
	ds_read_b128 v[228:231], v151 offset:52224
	ds_read_b128 v[232:235], v151 offset:53248
	ds_read_b128 v[236:239], v151 offset:54272
	ds_read_b128 v[240:243], v151 offset:55296
	ds_read_b128 v[244:247], v151 offset:56320
	global_load_lds_dwordx4 v[180:181], off
	s_add_i32 m0, s0, 0x2000
	s_add_u32 s86, s86, 0x40080
	v_lshl_add_u64 v[180:181], v[192:193], 0, s[58:59]
	s_addc_u32 s87, s87, 0
	s_add_i32 s0, s96, s1
	global_load_lds_dwordx4 v[180:181], off
	v_lshl_add_u64 v[180:181], s[86:87], 0, v[98:99]
	s_mov_b32 m0, s0
	s_nop 0
	global_load_lds_dwordx4 v[180:181], off
	v_lshl_add_u64 v[180:181], s[86:87], 0, v[134:135]
	s_add_i32 m0, s0, 0x2000
	s_nop 0
	global_load_lds_dwordx4 v[180:181], off
	v_lshl_add_u64 v[180:181], v[248:249], 0, s[58:59]
	s_mov_b32 m0, s42
	s_nop 0
	global_load_lds_dwordx4 v[180:181], off
	v_lshl_add_u64 v[180:181], v[250:251], 0, s[58:59]
	s_mov_b32 m0, s43
	s_nop 0
	global_load_lds_dwordx4 v[180:181], off
	s_waitcnt vmcnt(8)
	s_waitcnt lgkmcnt(0)
	s_barrier
	s_setprio 1
	s_waitcnt lgkmcnt(0)
	v_mfma_f32_16x16x32_bf16 v[60:63], v[140:143], v[188:191], v[60:63]
	v_mfma_f32_16x16x32_bf16 v[56:59], v[156:159], v[188:191], v[56:59]
	v_mfma_f32_16x16x32_bf16 v[44:47], v[140:143], v[224:227], v[44:47]
	v_mfma_f32_16x16x32_bf16 v[40:43], v[156:159], v[224:227], v[40:43]
	v_mfma_f32_16x16x32_bf16 v[28:31], v[140:143], v[232:235], v[28:31]
	v_mfma_f32_16x16x32_bf16 v[24:27], v[156:159], v[232:235], v[24:27]
	v_mfma_f32_16x16x32_bf16 v[12:15], v[140:143], v[240:243], v[12:15]
	v_mfma_f32_16x16x32_bf16 v[8:11], v[156:159], v[240:243], v[8:11]
	v_mfma_f32_16x16x32_bf16 v[60:63], v[152:155], v[220:223], v[60:63]
	v_mfma_f32_16x16x32_bf16 v[56:59], v[160:163], v[220:223], v[56:59]
	v_mfma_f32_16x16x32_bf16 v[44:47], v[152:155], v[228:231], v[44:47]
	v_mfma_f32_16x16x32_bf16 v[40:43], v[160:163], v[228:231], v[40:43]
	v_mfma_f32_16x16x32_bf16 v[28:31], v[152:155], v[236:239], v[28:31]
	v_mfma_f32_16x16x32_bf16 v[24:27], v[160:163], v[236:239], v[24:27]
	v_mfma_f32_16x16x32_bf16 v[12:15], v[152:155], v[244:247], v[12:15]
	v_mfma_f32_16x16x32_bf16 v[8:11], v[160:163], v[244:247], v[8:11]
	s_setprio 0
	s_setprio 1
	v_mfma_f32_16x16x32_bf16 v[52:55], v[164:167], v[188:191], v[52:55]
	v_mfma_f32_16x16x32_bf16 v[48:51], v[172:175], v[188:191], v[48:51]
	v_mfma_f32_16x16x32_bf16 v[36:39], v[164:167], v[224:227], v[36:39]
	v_mfma_f32_16x16x32_bf16 v[32:35], v[172:175], v[224:227], v[32:35]
	v_mfma_f32_16x16x32_bf16 v[20:23], v[164:167], v[232:235], v[20:23]
	v_mfma_f32_16x16x32_bf16 v[16:19], v[172:175], v[232:235], v[16:19]
	v_mfma_f32_16x16x32_bf16 v[4:7], v[164:167], v[240:243], v[4:7]
	v_mfma_f32_16x16x32_bf16 v[0:3], v[172:175], v[240:243], v[0:3]
	v_mfma_f32_16x16x32_bf16 v[52:55], v[168:171], v[220:223], v[52:55]
	v_mfma_f32_16x16x32_bf16 v[48:51], v[176:179], v[220:223], v[48:51]
	v_mfma_f32_16x16x32_bf16 v[36:39], v[168:171], v[228:231], v[36:39]
	v_mfma_f32_16x16x32_bf16 v[32:35], v[176:179], v[228:231], v[32:35]
	v_mfma_f32_16x16x32_bf16 v[20:23], v[168:171], v[236:239], v[20:23]
	v_mfma_f32_16x16x32_bf16 v[16:19], v[176:179], v[236:239], v[16:19]
	v_mfma_f32_16x16x32_bf16 v[4:7], v[168:171], v[244:247], v[4:7]
	v_mfma_f32_16x16x32_bf16 v[0:3], v[176:179], v[244:247], v[0:3]
	s_setprio 0
	s_barrier
	s_add_i32 s90, s90, 2
	s_add_u32 s84, s84, 0x100
	s_addc_u32 s85, s85, 0
	s_add_u32 s75, s75, 0x100
	s_addc_u32 s77, s77, 0
	s_cmp_gt_u32 s90, 13
	s_cbranch_scc0 .LBB0_232
	s_and_b64 vcc, exec, s[72:73]
	s_cbranch_vccz .LBB0_235
	s_barrier

.LBB0_309:
	s_add_u32 s84, s84, 0x80
	s_addc_u32 s85, s85, 0
	s_add_u32 s26, s86, 0x100
	v_mov_b64_e32 v[0:1], 0
	s_addc_u32 s27, s87, 0
	s_mov_b32 s0, 0
	s_waitcnt lgkmcnt(0)
	v_mov_b64_e32 v[2:3], 0
	v_mov_b64_e32 v[4:5], 0
	v_mov_b64_e32 v[6:7], 0
	v_mov_b64_e32 v[8:9], 0
	v_mov_b64_e32 v[10:11], 0
	v_mov_b64_e32 v[12:13], 0
	v_mov_b64_e32 v[14:15], 0
	v_mov_b64_e32 v[16:17], 0
	v_mov_b64_e32 v[18:19], 0
	v_mov_b64_e32 v[20:21], 0
	v_mov_b64_e32 v[22:23], 0
	v_mov_b64_e32 v[24:25], 0
	v_mov_b64_e32 v[26:27], 0
	v_mov_b64_e32 v[28:29], 0
	v_mov_b64_e32 v[30:31], 0
	v_mov_b64_e32 v[32:33], 0
	v_mov_b64_e32 v[34:35], 0
	v_mov_b64_e32 v[36:37], 0
	v_mov_b64_e32 v[38:39], 0
	v_mov_b64_e32 v[40:41], 0
	v_mov_b64_e32 v[42:43], 0
	v_mov_b64_e32 v[44:45], 0
	v_mov_b64_e32 v[46:47], 0
	v_mov_b64_e32 v[48:49], 0
	v_mov_b64_e32 v[50:51], 0
	v_mov_b64_e32 v[52:53], 0
	v_mov_b64_e32 v[54:55], 0
	v_mov_b64_e32 v[56:57], 0
	v_mov_b64_e32 v[58:59], 0
	v_mov_b64_e32 v[60:61], 0
	v_mov_b64_e32 v[62:63], 0
	v_mov_b64_e32 v[64:65], 0
	v_mov_b64_e32 v[66:67], 0
	v_mov_b64_e32 v[68:69], 0
	v_mov_b64_e32 v[70:71], 0
	v_mov_b64_e32 v[72:73], 0
	v_mov_b64_e32 v[74:75], 0
	v_mov_b64_e32 v[76:77], 0
	v_mov_b64_e32 v[78:79], 0
	v_mov_b64_e32 v[80:81], 0
	v_mov_b64_e32 v[82:83], 0
	v_mov_b64_e32 v[84:85], 0
	v_mov_b64_e32 v[86:87], 0
	v_mov_b64_e32 v[88:89], 0
	v_mov_b64_e32 v[90:91], 0
	v_mov_b64_e32 v[92:93], 0
	v_mov_b64_e32 v[94:95], 0
	v_mov_b64_e32 v[100:101], 0
	v_mov_b64_e32 v[102:103], 0
	v_mov_b64_e32 v[104:105], 0
	v_mov_b64_e32 v[106:107], 0
	v_mov_b64_e32 v[108:109], 0
	v_mov_b64_e32 v[110:111], 0
	v_mov_b64_e32 v[112:113], 0
	v_mov_b64_e32 v[114:115], 0
	v_mov_b64_e32 v[116:117], 0
	v_mov_b64_e32 v[118:119], 0
	v_mov_b64_e32 v[120:121], 0
	v_mov_b64_e32 v[122:123], 0
	v_mov_b64_e32 v[124:125], 0
	v_mov_b64_e32 v[126:127], 0
	v_mov_b64_e32 v[128:129], 0
	v_mov_b64_e32 v[130:131], 0
.LBB0_310:
	s_add_i32 s42, s0, 2
	s_add_u32 s66, s84, 0x80
	s_addc_u32 s86, s85, 0
	s_add_i32 s97, 0, 0x10000
	s_cmp_eq_u32 s88, s0
	s_cselect_b32 s87, s81, s86
	s_cselect_b32 s86, s80, s66
	s_cselect_b32 vcc_hi, s83, s27
	s_cselect_b32 vcc_lo, s82, s26
	s_add_i32 s0, 0, 0x14000
	v_add_u32_e32 v152, s97, v161
	v_add_u32_e32 v172, s0, v161
	ds_read_b128 v[132:135], v152
	ds_read_b128 v[136:139], v152 offset:1024
	ds_read_b128 v[148:151], v152 offset:2048
	ds_read_b128 v[152:155], v152 offset:3072
	ds_read_b128 v[156:159], v172
	ds_read_b128 v[164:167], v172 offset:1024
	ds_read_b128 v[168:171], v172 offset:2048
	ds_read_b128 v[172:175], v172 offset:3072
	v_lshl_add_u64 v[180:181], s[84:85], 0, v[144:145]
	s_add_i32 m0, s23, 0xc000
	ds_read_b128 v[176:179], v163
	ds_read_b128 v[188:191], v163 offset:1024
	ds_read_b128 v[220:223], v163 offset:2048
	ds_read_b128 v[224:227], v163 offset:3072
	ds_read_b128 v[228:231], v163 offset:4096
	ds_read_b128 v[232:235], v163 offset:5120
	ds_read_b128 v[236:239], v163 offset:6144
	ds_read_b128 v[240:243], v163 offset:7168
	global_load_lds_dwordx4 v[180:181], off
	v_lshl_add_u64 v[180:181], s[84:85], 0, v[146:147]
	s_add_i32 m0, s23, 0xe000
	s_nop 0
	global_load_lds_dwordx4 v[180:181], off
	s_waitcnt vmcnt(8)
	s_waitcnt lgkmcnt(0)
	s_barrier
	s_setprio 1
	s_waitcnt lgkmcnt(0)
	v_mfma_f32_16x16x32_bf16 v[128:131], v[132:135], v[176:179], v[128:131]
	v_mfma_f32_16x16x32_bf16 v[124:127], v[148:151], v[176:179], v[124:127]
	v_mfma_f32_16x16x32_bf16 v[112:115], v[132:135], v[220:223], v[112:115]
	v_mfma_f32_16x16x32_bf16 v[108:111], v[148:151], v[220:223], v[108:111]
	v_mfma_f32_16x16x32_bf16 v[92:95], v[132:135], v[228:231], v[92:95]
	v_mfma_f32_16x16x32_bf16 v[88:91], v[148:151], v[228:231], v[88:91]
	v_mfma_f32_16x16x32_bf16 v[76:79], v[132:135], v[236:239], v[76:79]
	v_mfma_f32_16x16x32_bf16 v[72:75], v[148:151], v[236:239], v[72:75]
	v_mfma_f32_16x16x32_bf16 v[128:131], v[136:139], v[188:191], v[128:131]
	v_mfma_f32_16x16x32_bf16 v[124:127], v[152:155], v[188:191], v[124:127]
	v_mfma_f32_16x16x32_bf16 v[112:115], v[136:139], v[224:227], v[112:115]
	v_mfma_f32_16x16x32_bf16 v[108:111], v[152:155], v[224:227], v[108:111]
	v_mfma_f32_16x16x32_bf16 v[92:95], v[136:139], v[232:235], v[92:95]
	v_mfma_f32_16x16x32_bf16 v[88:91], v[152:155], v[232:235], v[88:91]
	v_mfma_f32_16x16x32_bf16 v[76:79], v[136:139], v[240:243], v[76:79]
	v_mfma_f32_16x16x32_bf16 v[72:75], v[152:155], v[240:243], v[72:75]
	s_setprio 0
	s_setprio 1
	v_mfma_f32_16x16x32_bf16 v[120:123], v[156:159], v[176:179], v[120:123]
	v_mfma_f32_16x16x32_bf16 v[116:119], v[168:171], v[176:179], v[116:119]
	v_mfma_f32_16x16x32_bf16 v[104:107], v[156:159], v[220:223], v[104:107]
	v_mfma_f32_16x16x32_bf16 v[100:103], v[168:171], v[220:223], v[100:103]
	v_mfma_f32_16x16x32_bf16 v[84:87], v[156:159], v[228:231], v[84:87]
	v_mfma_f32_16x16x32_bf16 v[80:83], v[168:171], v[228:231], v[80:83]
	v_mfma_f32_16x16x32_bf16 v[68:71], v[156:159], v[236:239], v[68:71]
	v_mfma_f32_16x16x32_bf16 v[64:67], v[168:171], v[236:239], v[64:67]
	v_mfma_f32_16x16x32_bf16 v[120:123], v[164:167], v[188:191], v[120:123]
	v_mfma_f32_16x16x32_bf16 v[116:119], v[172:175], v[188:191], v[116:119]
	v_mfma_f32_16x16x32_bf16 v[104:107], v[164:167], v[224:227], v[104:107]
	v_mfma_f32_16x16x32_bf16 v[100:103], v[172:175], v[224:227], v[100:103]
	v_mfma_f32_16x16x32_bf16 v[84:87], v[164:167], v[232:235], v[84:87]
	v_mfma_f32_16x16x32_bf16 v[80:83], v[172:175], v[232:235], v[80:83]
	v_mfma_f32_16x16x32_bf16 v[68:71], v[164:167], v[240:243], v[68:71]
	v_mfma_f32_16x16x32_bf16 v[64:67], v[172:175], v[240:243], v[64:67]
	s_setprio 0
	s_barrier
	s_add_i32 s66, s97, s10
	v_lshl_add_u64 v[180:181], vcc, 0, v[98:99]
	s_mov_b32 m0, s66
	ds_read_b128 v[176:179], v163 offset:16384
	ds_read_b128 v[188:191], v163 offset:17408
	ds_read_b128 v[220:223], v163 offset:18432
	ds_read_b128 v[224:227], v163 offset:19456
	ds_read_b128 v[228:231], v163 offset:20480
	ds_read_b128 v[232:235], v163 offset:21504
	ds_read_b128 v[236:239], v163 offset:22528
	ds_read_b128 v[240:243], v163 offset:23552
	global_load_lds_dwordx4 v[180:181], off
	s_add_i32 m0, s66, 0x2000
	v_lshl_add_u64 v[192:193], vcc, 0, v[142:143]
	s_add_u32 vcc_lo, vcc_lo, s72
	s_addc_u32 vcc_hi, vcc_hi, 0
	s_add_i32 s0, s0, s10
	global_load_lds_dwordx4 v[192:193], off
	v_lshl_add_u64 v[244:245], vcc, 0, v[98:99]
	s_mov_b32 m0, s0
	v_lshl_add_u64 v[246:247], vcc, 0, v[142:143]
	global_load_lds_dwordx4 v[244:245], off
	s_add_i32 m0, s0, 0x2000
	v_lshl_add_u64 v[248:249], s[86:87], 0, v[96:97]
	global_load_lds_dwordx4 v[246:247], off
	s_mov_b32 m0, s23
	v_lshl_add_u64 v[250:251], s[86:87], 0, v[140:141]
	global_load_lds_dwordx4 v[248:249], off
	s_mov_b32 m0, s33
	s_nop 0
	global_load_lds_dwordx4 v[250:251], off
	s_waitcnt vmcnt(8)
	s_waitcnt lgkmcnt(0)
	s_barrier
	s_setprio 1
	s_waitcnt lgkmcnt(0)
	v_mfma_f32_16x16x32_bf16 v[60:63], v[132:135], v[176:179], v[60:63]
	v_mfma_f32_16x16x32_bf16 v[56:59], v[148:151], v[176:179], v[56:59]
	v_mfma_f32_16x16x32_bf16 v[44:47], v[132:135], v[220:223], v[44:47]
	v_mfma_f32_16x16x32_bf16 v[40:43], v[148:151], v[220:223], v[40:43]
	v_mfma_f32_16x16x32_bf16 v[28:31], v[132:135], v[228:231], v[28:31]
	v_mfma_f32_16x16x32_bf16 v[24:27], v[148:151], v[228:231], v[24:27]
	v_mfma_f32_16x16x32_bf16 v[12:15], v[132:135], v[236:239], v[12:15]
	v_mfma_f32_16x16x32_bf16 v[8:11], v[148:151], v[236:239], v[8:11]
	v_mfma_f32_16x16x32_bf16 v[60:63], v[136:139], v[188:191], v[60:63]
	v_mfma_f32_16x16x32_bf16 v[56:59], v[152:155], v[188:191], v[56:59]
	v_mfma_f32_16x16x32_bf16 v[44:47], v[136:139], v[224:227], v[44:47]
	v_mfma_f32_16x16x32_bf16 v[40:43], v[152:155], v[224:227], v[40:43]
	v_mfma_f32_16x16x32_bf16 v[28:31], v[136:139], v[232:235], v[28:31]
	v_mfma_f32_16x16x32_bf16 v[24:27], v[152:155], v[232:235], v[24:27]
	v_mfma_f32_16x16x32_bf16 v[12:15], v[136:139], v[240:243], v[12:15]
	v_mfma_f32_16x16x32_bf16 v[8:11], v[152:155], v[240:243], v[8:11]
	s_setprio 0
	s_setprio 1
	v_mfma_f32_16x16x32_bf16 v[52:55], v[156:159], v[176:179], v[52:55]
	v_mfma_f32_16x16x32_bf16 v[48:51], v[168:171], v[176:179], v[48:51]
	v_mfma_f32_16x16x32_bf16 v[36:39], v[156:159], v[220:223], v[36:39]
	v_mfma_f32_16x16x32_bf16 v[32:35], v[168:171], v[220:223], v[32:35]
	v_mfma_f32_16x16x32_bf16 v[20:23], v[156:159], v[228:231], v[20:23]
	v_mfma_f32_16x16x32_bf16 v[16:19], v[168:171], v[228:231], v[16:19]
	v_mfma_f32_16x16x32_bf16 v[4:7], v[156:159], v[236:239], v[4:7]
	v_mfma_f32_16x16x32_bf16 v[0:3], v[168:171], v[236:239], v[0:3]
	v_mfma_f32_16x16x32_bf16 v[52:55], v[164:167], v[188:191], v[52:55]
	v_mfma_f32_16x16x32_bf16 v[48:51], v[172:175], v[188:191], v[48:51]
	v_mfma_f32_16x16x32_bf16 v[36:39], v[164:167], v[224:227], v[36:39]
	v_mfma_f32_16x16x32_bf16 v[32:35], v[172:175], v[224:227], v[32:35]
	v_mfma_f32_16x16x32_bf16 v[20:23], v[164:167], v[232:235], v[20:23]
	v_mfma_f32_16x16x32_bf16 v[16:19], v[172:175], v[232:235], v[16:19]
	v_mfma_f32_16x16x32_bf16 v[4:7], v[164:167], v[240:243], v[4:7]
	v_mfma_f32_16x16x32_bf16 v[0:3], v[172:175], v[240:243], v[0:3]
	s_setprio 0
	s_barrier
	s_add_i32 s0, 0, 0x18000
	s_add_i32 s66, 0, 0x1c000
	v_add_u32_e32 v152, s0, v161
	v_add_u32_e32 v172, s66, v161
	ds_read_b128 v[132:135], v152
	ds_read_b128 v[136:139], v152 offset:1024
	ds_read_b128 v[148:151], v152 offset:2048
	ds_read_b128 v[152:155], v152 offset:3072
	ds_read_b128 v[156:159], v172
	ds_read_b128 v[164:167], v172 offset:1024
	ds_read_b128 v[168:171], v172 offset:2048
	ds_read_b128 v[172:175], v172 offset:3072
	s_add_u32 s86, s86, s72
	s_addc_u32 s87, s87, 0
	s_mov_b32 m0, s43
	v_lshl_add_u64 v[252:253], s[86:87], 0, v[96:97]
	ds_read_b128 v[176:179], v163 offset:32768
	ds_read_b128 v[188:191], v163 offset:33792
	ds_read_b128 v[220:223], v163 offset:34816
	ds_read_b128 v[224:227], v163 offset:35840
	ds_read_b128 v[228:231], v163 offset:36864
	ds_read_b128 v[232:235], v163 offset:37888
	ds_read_b128 v[236:239], v163 offset:38912
	ds_read_b128 v[240:243], v163 offset:39936
	global_load_lds_dwordx4 v[252:253], off
	v_lshl_add_u64 v[252:253], s[86:87], 0, v[140:141]
	s_mov_b32 m0, s44
	s_nop 0
	global_load_lds_dwordx4 v[252:253], off
	s_waitcnt vmcnt(8)
	s_waitcnt lgkmcnt(0)
	s_barrier
	s_setprio 1
	s_waitcnt lgkmcnt(0)
	v_mfma_f32_16x16x32_bf16 v[128:131], v[132:135], v[176:179], v[128:131]
	v_mfma_f32_16x16x32_bf16 v[124:127], v[148:151], v[176:179], v[124:127]
	v_mfma_f32_16x16x32_bf16 v[112:115], v[132:135], v[220:223], v[112:115]
	v_mfma_f32_16x16x32_bf16 v[108:111], v[148:151], v[220:223], v[108:111]
	v_mfma_f32_16x16x32_bf16 v[92:95], v[132:135], v[228:231], v[92:95]
	v_mfma_f32_16x16x32_bf16 v[88:91], v[148:151], v[228:231], v[88:91]
	v_mfma_f32_16x16x32_bf16 v[76:79], v[132:135], v[236:239], v[76:79]
	v_mfma_f32_16x16x32_bf16 v[72:75], v[148:151], v[236:239], v[72:75]
	v_mfma_f32_16x16x32_bf16 v[128:131], v[136:139], v[188:191], v[128:131]
	v_mfma_f32_16x16x32_bf16 v[124:127], v[152:155], v[188:191], v[124:127]
	v_mfma_f32_16x16x32_bf16 v[112:115], v[136:139], v[224:227], v[112:115]
	v_mfma_f32_16x16x32_bf16 v[108:111], v[152:155], v[224:227], v[108:111]
	v_mfma_f32_16x16x32_bf16 v[92:95], v[136:139], v[232:235], v[92:95]
	v_mfma_f32_16x16x32_bf16 v[88:91], v[152:155], v[232:235], v[88:91]
	v_mfma_f32_16x16x32_bf16 v[76:79], v[136:139], v[240:243], v[76:79]
	v_mfma_f32_16x16x32_bf16 v[72:75], v[152:155], v[240:243], v[72:75]
	s_setprio 0
	s_setprio 1
	v_mfma_f32_16x16x32_bf16 v[120:123], v[156:159], v[176:179], v[120:123]
	v_mfma_f32_16x16x32_bf16 v[116:119], v[168:171], v[176:179], v[116:119]
	v_mfma_f32_16x16x32_bf16 v[104:107], v[156:159], v[220:223], v[104:107]
	v_mfma_f32_16x16x32_bf16 v[100:103], v[168:171], v[220:223], v[100:103]
	v_mfma_f32_16x16x32_bf16 v[84:87], v[156:159], v[228:231], v[84:87]
	v_mfma_f32_16x16x32_bf16 v[80:83], v[168:171], v[228:231], v[80:83]
	v_mfma_f32_16x16x32_bf16 v[68:71], v[156:159], v[236:239], v[68:71]
	v_mfma_f32_16x16x32_bf16 v[64:67], v[168:171], v[236:239], v[64:67]
	v_mfma_f32_16x16x32_bf16 v[120:123], v[164:167], v[188:191], v[120:123]
	v_mfma_f32_16x16x32_bf16 v[116:119], v[172:175], v[188:191], v[116:119]
	v_mfma_f32_16x16x32_bf16 v[104:107], v[164:167], v[224:227], v[104:107]
	v_mfma_f32_16x16x32_bf16 v[100:103], v[172:175], v[224:227], v[100:103]
	v_mfma_f32_16x16x32_bf16 v[84:87], v[164:167], v[232:235], v[84:87]
	v_mfma_f32_16x16x32_bf16 v[80:83], v[172:175], v[232:235], v[80:83]
	v_mfma_f32_16x16x32_bf16 v[68:71], v[164:167], v[240:243], v[68:71]
	v_mfma_f32_16x16x32_bf16 v[64:67], v[172:175], v[240:243], v[64:67]
	s_setprio 0
	s_barrier
	s_add_i32 s0, s0, s10
	v_lshl_add_u64 v[180:181], v[180:181], 0, s[58:59]
	s_mov_b32 m0, s0
	ds_read_b128 v[176:179], v163 offset:49152
	ds_read_b128 v[188:191], v163 offset:50176
	ds_read_b128 v[220:223], v163 offset:51200
	ds_read_b128 v[224:227], v163 offset:52224
	ds_read_b128 v[228:231], v163 offset:53248
	ds_read_b128 v[232:235], v163 offset:54272
	ds_read_b128 v[236:239], v163 offset:55296
	ds_read_b128 v[240:243], v163 offset:56320
	global_load_lds_dwordx4 v[180:181], off
	v_lshl_add_u64 v[180:181], v[192:193], 0, s[58:59]
	s_add_i32 m0, s0, 0x2000
	s_add_i32 s0, s66, s10
	global_load_lds_dwordx4 v[180:181], off
	v_lshl_add_u64 v[180:181], v[244:245], 0, s[58:59]
	s_mov_b32 m0, s0
	s_nop 0
	global_load_lds_dwordx4 v[180:181], off
	v_lshl_add_u64 v[180:181], v[246:247], 0, s[58:59]
	s_add_i32 m0, s0, 0x2000
	s_nop 0
	global_load_lds_dwordx4 v[180:181], off
	v_lshl_add_u64 v[180:181], v[248:249], 0, s[58:59]
	s_mov_b32 m0, s47
	s_nop 0
	global_load_lds_dwordx4 v[180:181], off
	v_lshl_add_u64 v[180:181], v[250:251], 0, s[58:59]
	s_mov_b32 m0, s56
	s_nop 0
	global_load_lds_dwordx4 v[180:181], off
	s_waitcnt vmcnt(8)
	s_waitcnt lgkmcnt(0)
	s_barrier
	s_setprio 1
	s_waitcnt lgkmcnt(0)
	v_mfma_f32_16x16x32_bf16 v[60:63], v[132:135], v[176:179], v[60:63]
	v_mfma_f32_16x16x32_bf16 v[56:59], v[148:151], v[176:179], v[56:59]
	v_mfma_f32_16x16x32_bf16 v[44:47], v[132:135], v[220:223], v[44:47]
	v_mfma_f32_16x16x32_bf16 v[40:43], v[148:151], v[220:223], v[40:43]
	v_mfma_f32_16x16x32_bf16 v[28:31], v[132:135], v[228:231], v[28:31]
	v_mfma_f32_16x16x32_bf16 v[24:27], v[148:151], v[228:231], v[24:27]
	v_mfma_f32_16x16x32_bf16 v[12:15], v[132:135], v[236:239], v[12:15]
	v_mfma_f32_16x16x32_bf16 v[8:11], v[148:151], v[236:239], v[8:11]
	v_mfma_f32_16x16x32_bf16 v[60:63], v[136:139], v[188:191], v[60:63]
	v_mfma_f32_16x16x32_bf16 v[56:59], v[152:155], v[188:191], v[56:59]
	v_mfma_f32_16x16x32_bf16 v[44:47], v[136:139], v[224:227], v[44:47]
	v_mfma_f32_16x16x32_bf16 v[40:43], v[152:155], v[224:227], v[40:43]
	v_mfma_f32_16x16x32_bf16 v[28:31], v[136:139], v[232:235], v[28:31]
	v_mfma_f32_16x16x32_bf16 v[24:27], v[152:155], v[232:235], v[24:27]
	v_mfma_f32_16x16x32_bf16 v[12:15], v[136:139], v[240:243], v[12:15]
	v_mfma_f32_16x16x32_bf16 v[8:11], v[152:155], v[240:243], v[8:11]
	s_setprio 0
	s_setprio 1
	v_mfma_f32_16x16x32_bf16 v[52:55], v[156:159], v[176:179], v[52:55]
	v_mfma_f32_16x16x32_bf16 v[48:51], v[168:171], v[176:179], v[48:51]
	v_mfma_f32_16x16x32_bf16 v[36:39], v[156:159], v[220:223], v[36:39]
	v_mfma_f32_16x16x32_bf16 v[32:35], v[168:171], v[220:223], v[32:35]
	v_mfma_f32_16x16x32_bf16 v[20:23], v[156:159], v[228:231], v[20:23]
	v_mfma_f32_16x16x32_bf16 v[16:19], v[168:171], v[228:231], v[16:19]
	v_mfma_f32_16x16x32_bf16 v[4:7], v[156:159], v[236:239], v[4:7]
	v_mfma_f32_16x16x32_bf16 v[0:3], v[168:171], v[236:239], v[0:3]
	v_mfma_f32_16x16x32_bf16 v[52:55], v[164:167], v[188:191], v[52:55]
	v_mfma_f32_16x16x32_bf16 v[48:51], v[172:175], v[188:191], v[48:51]
	v_mfma_f32_16x16x32_bf16 v[36:39], v[164:167], v[224:227], v[36:39]
	v_mfma_f32_16x16x32_bf16 v[32:35], v[172:175], v[224:227], v[32:35]
	v_mfma_f32_16x16x32_bf16 v[20:23], v[164:167], v[232:235], v[20:23]
	v_mfma_f32_16x16x32_bf16 v[16:19], v[172:175], v[232:235], v[16:19]
	v_mfma_f32_16x16x32_bf16 v[4:7], v[164:167], v[240:243], v[4:7]
	v_mfma_f32_16x16x32_bf16 v[0:3], v[172:175], v[240:243], v[0:3]
	s_setprio 0
	s_barrier
	s_add_u32 s84, s84, 0x100
	s_addc_u32 s85, s85, 0
	s_add_u32 s26, s26, 0x100
	s_addc_u32 s27, s27, 0
	s_cmp_ge_u32 s42, s67
	s_mov_b32 s0, s42
	s_cbranch_scc0 .LBB0_310
	s_and_b64 vcc, exec, s[78:79]
	s_cbranch_vccz .LBB0_313
	s_barrier

.LBB0_345:
	s_ashr_i32 s71, s70, 31
	s_lshl_b64 s[56:57], s[70:71], 19
	s_add_u32 s74, s12, s56
	s_addc_u32 s75, s13, s57
	s_and_b64 s[56:57], s[72:73], exec
	s_cselect_b32 s27, s75, s79
	s_cselect_b32 s42, s74, s78
	s_ashr_i32 s69, s68, 31
	s_lshl_b64 s[56:57], s[68:69], 19
	s_add_u32 s76, s4, s56
	s_addc_u32 s77, s5, s57
	s_and_b64 s[56:57], s[72:73], exec
	s_cselect_b32 s56, s77, s81
	s_cselect_b32 s57, s76, s80
	s_add_u32 s78, s78, 0x40080
	s_addc_u32 s79, s79, 0
	s_add_u32 s69, s80, 0x100
	v_mov_b64_e32 v[0:1], 0
	s_addc_u32 s71, s81, 0
	s_mov_b32 s84, -2
	v_mov_b64_e32 v[2:3], 0
	v_mov_b64_e32 v[4:5], 0
	v_mov_b64_e32 v[6:7], 0
	v_mov_b64_e32 v[8:9], 0
	v_mov_b64_e32 v[10:11], 0
	v_mov_b64_e32 v[12:13], 0
	v_mov_b64_e32 v[14:15], 0
	v_mov_b64_e32 v[16:17], 0
	v_mov_b64_e32 v[18:19], 0
	v_mov_b64_e32 v[20:21], 0
	v_mov_b64_e32 v[22:23], 0
	v_mov_b64_e32 v[24:25], 0
	v_mov_b64_e32 v[26:27], 0
	v_mov_b64_e32 v[28:29], 0
	v_mov_b64_e32 v[30:31], 0
	v_mov_b64_e32 v[32:33], 0
	v_mov_b64_e32 v[34:35], 0
	v_mov_b64_e32 v[36:37], 0
	v_mov_b64_e32 v[38:39], 0
	v_mov_b64_e32 v[40:41], 0
	v_mov_b64_e32 v[42:43], 0
	v_mov_b64_e32 v[44:45], 0
	v_mov_b64_e32 v[46:47], 0
	v_mov_b64_e32 v[48:49], 0
	v_mov_b64_e32 v[50:51], 0
	v_mov_b64_e32 v[52:53], 0
	v_mov_b64_e32 v[54:55], 0
	v_mov_b64_e32 v[56:57], 0
	v_mov_b64_e32 v[58:59], 0
	v_mov_b64_e32 v[60:61], 0
	v_mov_b64_e32 v[62:63], 0
	v_mov_b64_e32 v[64:65], 0
	v_mov_b64_e32 v[66:67], 0
	v_mov_b64_e32 v[68:69], 0
	v_mov_b64_e32 v[70:71], 0
	v_mov_b64_e32 v[72:73], 0
	v_mov_b64_e32 v[74:75], 0
	v_mov_b64_e32 v[76:77], 0
	v_mov_b64_e32 v[78:79], 0
	v_mov_b64_e32 v[80:81], 0
	v_mov_b64_e32 v[82:83], 0
	v_mov_b64_e32 v[84:85], 0
	v_mov_b64_e32 v[86:87], 0
	v_mov_b64_e32 v[88:89], 0
	v_mov_b64_e32 v[90:91], 0
	v_mov_b64_e32 v[92:93], 0
	v_mov_b64_e32 v[94:95], 0
	v_mov_b64_e32 v[100:101], 0
	v_mov_b64_e32 v[102:103], 0
	v_mov_b64_e32 v[104:105], 0
	v_mov_b64_e32 v[106:107], 0
	v_mov_b64_e32 v[108:109], 0
	v_mov_b64_e32 v[110:111], 0
	v_mov_b64_e32 v[112:113], 0
	v_mov_b64_e32 v[114:115], 0
	v_mov_b64_e32 v[116:117], 0
	v_mov_b64_e32 v[118:119], 0
	v_mov_b64_e32 v[120:121], 0
	v_mov_b64_e32 v[122:123], 0
	v_mov_b64_e32 v[124:125], 0
	v_mov_b64_e32 v[126:127], 0
	v_mov_b64_e32 v[128:129], 0
	v_mov_b64_e32 v[130:131], 0
.LBB0_346:
	s_add_u32 s80, s78, 0xfffc0080
	s_addc_u32 s81, s79, -1
	s_add_i32 s85, 0, 0x10000
	s_cmp_eq_u32 s84, 12
	s_cselect_b32 s83, s27, s81
	s_cselect_b32 s82, s42, s80
	s_cselect_b32 s81, s56, s71
	s_cselect_b32 s80, s57, s69
	s_add_i32 s88, 0, 0x14000
	v_add_u32_e32 v160, s85, v145
	v_add_u32_e32 v176, s88, v145
	ds_read_b128 v[140:143], v160
	ds_read_b128 v[152:155], v160 offset:1024
	ds_read_b128 v[156:159], v160 offset:2048
	ds_read_b128 v[160:163], v160 offset:3072
	ds_read_b128 v[164:167], v176
	ds_read_b128 v[168:171], v176 offset:1024
	ds_read_b128 v[172:175], v176 offset:2048
	ds_read_b128 v[176:179], v176 offset:3072
	v_lshl_add_u64 v[180:181], s[78:79], 0, v[136:137]
	s_add_i32 m0, s11, 0xc000
	ds_read_b128 v[188:191], v151
	ds_read_b128 v[220:223], v151 offset:1024
	ds_read_b128 v[224:227], v151 offset:2048
	ds_read_b128 v[228:231], v151 offset:3072
	ds_read_b128 v[232:235], v151 offset:4096
	ds_read_b128 v[236:239], v151 offset:5120
	ds_read_b128 v[240:243], v151 offset:6144
	ds_read_b128 v[244:247], v151 offset:7168
	global_load_lds_dwordx4 v[180:181], off
	v_lshl_add_u64 v[180:181], s[78:79], 0, v[138:139]
	s_add_i32 m0, s11, 0xe000
	s_nop 0
	global_load_lds_dwordx4 v[180:181], off
	s_waitcnt vmcnt(8)
	s_waitcnt lgkmcnt(0)
	s_barrier
	s_setprio 1
	s_waitcnt lgkmcnt(0)
	v_mfma_f32_16x16x32_bf16 v[128:131], v[140:143], v[188:191], v[128:131]
	v_mfma_f32_16x16x32_bf16 v[120:123], v[156:159], v[188:191], v[120:123]
	v_mfma_f32_16x16x32_bf16 v[112:115], v[140:143], v[224:227], v[112:115]
	v_mfma_f32_16x16x32_bf16 v[104:107], v[156:159], v[224:227], v[104:107]
	v_mfma_f32_16x16x32_bf16 v[92:95], v[140:143], v[232:235], v[92:95]
	v_mfma_f32_16x16x32_bf16 v[84:87], v[156:159], v[232:235], v[84:87]
	v_mfma_f32_16x16x32_bf16 v[76:79], v[140:143], v[240:243], v[76:79]
	v_mfma_f32_16x16x32_bf16 v[68:71], v[156:159], v[240:243], v[68:71]
	v_mfma_f32_16x16x32_bf16 v[128:131], v[152:155], v[220:223], v[128:131]
	v_mfma_f32_16x16x32_bf16 v[120:123], v[160:163], v[220:223], v[120:123]
	v_mfma_f32_16x16x32_bf16 v[112:115], v[152:155], v[228:231], v[112:115]
	v_mfma_f32_16x16x32_bf16 v[104:107], v[160:163], v[228:231], v[104:107]
	v_mfma_f32_16x16x32_bf16 v[92:95], v[152:155], v[236:239], v[92:95]
	v_mfma_f32_16x16x32_bf16 v[84:87], v[160:163], v[236:239], v[84:87]
	v_mfma_f32_16x16x32_bf16 v[76:79], v[152:155], v[244:247], v[76:79]
	v_mfma_f32_16x16x32_bf16 v[68:71], v[160:163], v[244:247], v[68:71]
	s_setprio 0
	s_setprio 1
	v_mfma_f32_16x16x32_bf16 v[124:127], v[164:167], v[188:191], v[124:127]
	v_mfma_f32_16x16x32_bf16 v[116:119], v[172:175], v[188:191], v[116:119]
	v_mfma_f32_16x16x32_bf16 v[108:111], v[164:167], v[224:227], v[108:111]
	v_mfma_f32_16x16x32_bf16 v[100:103], v[172:175], v[224:227], v[100:103]
	v_mfma_f32_16x16x32_bf16 v[88:91], v[164:167], v[232:235], v[88:91]
	v_mfma_f32_16x16x32_bf16 v[80:83], v[172:175], v[232:235], v[80:83]
	v_mfma_f32_16x16x32_bf16 v[72:75], v[164:167], v[240:243], v[72:75]
	v_mfma_f32_16x16x32_bf16 v[64:67], v[172:175], v[240:243], v[64:67]
	v_mfma_f32_16x16x32_bf16 v[124:127], v[168:171], v[220:223], v[124:127]
	v_mfma_f32_16x16x32_bf16 v[116:119], v[176:179], v[220:223], v[116:119]
	v_mfma_f32_16x16x32_bf16 v[108:111], v[168:171], v[228:231], v[108:111]
	v_mfma_f32_16x16x32_bf16 v[100:103], v[176:179], v[228:231], v[100:103]
	v_mfma_f32_16x16x32_bf16 v[88:91], v[168:171], v[236:239], v[88:91]
	v_mfma_f32_16x16x32_bf16 v[80:83], v[176:179], v[236:239], v[80:83]
	v_mfma_f32_16x16x32_bf16 v[72:75], v[168:171], v[244:247], v[72:75]
	v_mfma_f32_16x16x32_bf16 v[64:67], v[176:179], v[244:247], v[64:67]
	s_setprio 0
	s_barrier
	s_add_i32 s85, s85, s10
	v_lshl_add_u64 v[180:181], s[80:81], 0, v[98:99]
	s_mov_b32 m0, s85
	ds_read_b128 v[188:191], v151 offset:16384
	ds_read_b128 v[220:223], v151 offset:17408
	ds_read_b128 v[224:227], v151 offset:18432
	ds_read_b128 v[228:231], v151 offset:19456
	ds_read_b128 v[232:235], v151 offset:20480
	ds_read_b128 v[236:239], v151 offset:21504
	ds_read_b128 v[240:243], v151 offset:22528
	ds_read_b128 v[244:247], v151 offset:23552
	global_load_lds_dwordx4 v[180:181], off
	s_add_i32 m0, s85, 0x2000
	s_add_u32 s86, s80, 0x40000
	v_lshl_add_u64 v[192:193], s[80:81], 0, v[134:135]
	s_addc_u32 s87, s81, 0
	s_add_i32 s85, s88, s10
	global_load_lds_dwordx4 v[192:193], off
	v_lshl_add_u64 v[248:249], s[86:87], 0, v[98:99]
	s_mov_b32 m0, s85
	v_lshl_add_u64 v[250:251], s[82:83], 0, v[132:133]
	global_load_lds_dwordx4 v[248:249], off
	v_lshl_add_u64 v[248:249], s[86:87], 0, v[134:135]
	s_add_i32 m0, s85, 0x2000
	s_nop 0
	global_load_lds_dwordx4 v[248:249], off
	v_lshl_add_u64 v[248:249], s[82:83], 0, v[96:97]
	s_mov_b32 m0, s11
	s_nop 0
	global_load_lds_dwordx4 v[248:249], off
	s_mov_b32 m0, s20
	s_nop 0
	global_load_lds_dwordx4 v[250:251], off
	s_waitcnt vmcnt(8)
	s_waitcnt lgkmcnt(0)
	s_barrier
	s_setprio 1
	s_waitcnt lgkmcnt(0)
	v_mfma_f32_16x16x32_bf16 v[60:63], v[140:143], v[188:191], v[60:63]
	v_mfma_f32_16x16x32_bf16 v[52:55], v[156:159], v[188:191], v[52:55]
	v_mfma_f32_16x16x32_bf16 v[44:47], v[140:143], v[224:227], v[44:47]
	v_mfma_f32_16x16x32_bf16 v[36:39], v[156:159], v[224:227], v[36:39]
	v_mfma_f32_16x16x32_bf16 v[28:31], v[140:143], v[232:235], v[28:31]
	v_mfma_f32_16x16x32_bf16 v[20:23], v[156:159], v[232:235], v[20:23]
	v_mfma_f32_16x16x32_bf16 v[12:15], v[140:143], v[240:243], v[12:15]
	v_mfma_f32_16x16x32_bf16 v[4:7], v[156:159], v[240:243], v[4:7]
	v_mfma_f32_16x16x32_bf16 v[60:63], v[152:155], v[220:223], v[60:63]
	v_mfma_f32_16x16x32_bf16 v[52:55], v[160:163], v[220:223], v[52:55]
	v_mfma_f32_16x16x32_bf16 v[44:47], v[152:155], v[228:231], v[44:47]
	v_mfma_f32_16x16x32_bf16 v[36:39], v[160:163], v[228:231], v[36:39]
	v_mfma_f32_16x16x32_bf16 v[28:31], v[152:155], v[236:239], v[28:31]
	v_mfma_f32_16x16x32_bf16 v[20:23], v[160:163], v[236:239], v[20:23]
	v_mfma_f32_16x16x32_bf16 v[12:15], v[152:155], v[244:247], v[12:15]
	v_mfma_f32_16x16x32_bf16 v[4:7], v[160:163], v[244:247], v[4:7]
	s_setprio 0
	s_setprio 1
	v_mfma_f32_16x16x32_bf16 v[56:59], v[164:167], v[188:191], v[56:59]
	v_mfma_f32_16x16x32_bf16 v[48:51], v[172:175], v[188:191], v[48:51]
	v_mfma_f32_16x16x32_bf16 v[40:43], v[164:167], v[224:227], v[40:43]
	v_mfma_f32_16x16x32_bf16 v[32:35], v[172:175], v[224:227], v[32:35]
	v_mfma_f32_16x16x32_bf16 v[24:27], v[164:167], v[232:235], v[24:27]
	v_mfma_f32_16x16x32_bf16 v[16:19], v[172:175], v[232:235], v[16:19]
	v_mfma_f32_16x16x32_bf16 v[8:11], v[164:167], v[240:243], v[8:11]
	v_mfma_f32_16x16x32_bf16 v[0:3], v[172:175], v[240:243], v[0:3]
	v_mfma_f32_16x16x32_bf16 v[56:59], v[168:171], v[220:223], v[56:59]
	v_mfma_f32_16x16x32_bf16 v[48:51], v[176:179], v[220:223], v[48:51]
	v_mfma_f32_16x16x32_bf16 v[40:43], v[168:171], v[228:231], v[40:43]
	v_mfma_f32_16x16x32_bf16 v[32:35], v[176:179], v[228:231], v[32:35]
	v_mfma_f32_16x16x32_bf16 v[24:27], v[168:171], v[236:239], v[24:27]
	v_mfma_f32_16x16x32_bf16 v[16:19], v[176:179], v[236:239], v[16:19]
	v_mfma_f32_16x16x32_bf16 v[8:11], v[168:171], v[244:247], v[8:11]
	v_mfma_f32_16x16x32_bf16 v[0:3], v[176:179], v[244:247], v[0:3]
	s_setprio 0
	s_barrier
	s_add_i32 s85, 0, 0x18000
	s_add_i32 s86, 0, 0x1c000
	v_add_u32_e32 v160, s85, v145
	v_add_u32_e32 v176, s86, v145
	ds_read_b128 v[140:143], v160
	ds_read_b128 v[152:155], v160 offset:1024
	ds_read_b128 v[156:159], v160 offset:2048
	ds_read_b128 v[160:163], v160 offset:3072
	ds_read_b128 v[164:167], v176
	ds_read_b128 v[168:171], v176 offset:1024
	ds_read_b128 v[172:175], v176 offset:2048
	ds_read_b128 v[176:179], v176 offset:3072
	s_add_u32 s82, s82, 0x40000
	s_addc_u32 s83, s83, 0
	s_mov_b32 m0, s22
	v_lshl_add_u64 v[252:253], s[82:83], 0, v[96:97]
	ds_read_b128 v[188:191], v151 offset:32768
	ds_read_b128 v[220:223], v151 offset:33792
	ds_read_b128 v[224:227], v151 offset:34816
	ds_read_b128 v[228:231], v151 offset:35840
	ds_read_b128 v[232:235], v151 offset:36864
	ds_read_b128 v[236:239], v151 offset:37888
	ds_read_b128 v[240:243], v151 offset:38912
	ds_read_b128 v[244:247], v151 offset:39936
	global_load_lds_dwordx4 v[252:253], off
	v_lshl_add_u64 v[252:253], s[82:83], 0, v[132:133]
	s_mov_b32 m0, s23
	s_nop 0
	global_load_lds_dwordx4 v[252:253], off
	s_waitcnt vmcnt(8)
	s_waitcnt lgkmcnt(0)
	s_barrier
	s_setprio 1
	s_waitcnt lgkmcnt(0)
	v_mfma_f32_16x16x32_bf16 v[128:131], v[140:143], v[188:191], v[128:131]
	v_mfma_f32_16x16x32_bf16 v[120:123], v[156:159], v[188:191], v[120:123]
	v_mfma_f32_16x16x32_bf16 v[112:115], v[140:143], v[224:227], v[112:115]
	v_mfma_f32_16x16x32_bf16 v[104:107], v[156:159], v[224:227], v[104:107]
	v_mfma_f32_16x16x32_bf16 v[92:95], v[140:143], v[232:235], v[92:95]
	v_mfma_f32_16x16x32_bf16 v[84:87], v[156:159], v[232:235], v[84:87]
	v_mfma_f32_16x16x32_bf16 v[76:79], v[140:143], v[240:243], v[76:79]
	v_mfma_f32_16x16x32_bf16 v[68:71], v[156:159], v[240:243], v[68:71]
	v_mfma_f32_16x16x32_bf16 v[128:131], v[152:155], v[220:223], v[128:131]
	v_mfma_f32_16x16x32_bf16 v[120:123], v[160:163], v[220:223], v[120:123]
	v_mfma_f32_16x16x32_bf16 v[112:115], v[152:155], v[228:231], v[112:115]
	v_mfma_f32_16x16x32_bf16 v[104:107], v[160:163], v[228:231], v[104:107]
	v_mfma_f32_16x16x32_bf16 v[92:95], v[152:155], v[236:239], v[92:95]
	v_mfma_f32_16x16x32_bf16 v[84:87], v[160:163], v[236:239], v[84:87]
	v_mfma_f32_16x16x32_bf16 v[76:79], v[152:155], v[244:247], v[76:79]
	v_mfma_f32_16x16x32_bf16 v[68:71], v[160:163], v[244:247], v[68:71]
	s_setprio 0
	s_setprio 1
	v_mfma_f32_16x16x32_bf16 v[124:127], v[164:167], v[188:191], v[124:127]
	v_mfma_f32_16x16x32_bf16 v[116:119], v[172:175], v[188:191], v[116:119]
	v_mfma_f32_16x16x32_bf16 v[108:111], v[164:167], v[224:227], v[108:111]
	v_mfma_f32_16x16x32_bf16 v[100:103], v[172:175], v[224:227], v[100:103]
	v_mfma_f32_16x16x32_bf16 v[88:91], v[164:167], v[232:235], v[88:91]
	v_mfma_f32_16x16x32_bf16 v[80:83], v[172:175], v[232:235], v[80:83]
	v_mfma_f32_16x16x32_bf16 v[72:75], v[164:167], v[240:243], v[72:75]
	v_mfma_f32_16x16x32_bf16 v[64:67], v[172:175], v[240:243], v[64:67]
	v_mfma_f32_16x16x32_bf16 v[124:127], v[168:171], v[220:223], v[124:127]
	v_mfma_f32_16x16x32_bf16 v[116:119], v[176:179], v[220:223], v[116:119]
	v_mfma_f32_16x16x32_bf16 v[108:111], v[168:171], v[228:231], v[108:111]
	v_mfma_f32_16x16x32_bf16 v[100:103], v[176:179], v[228:231], v[100:103]
	v_mfma_f32_16x16x32_bf16 v[88:91], v[168:171], v[236:239], v[88:91]
	v_mfma_f32_16x16x32_bf16 v[80:83], v[176:179], v[236:239], v[80:83]
	v_mfma_f32_16x16x32_bf16 v[72:75], v[168:171], v[244:247], v[72:75]
	v_mfma_f32_16x16x32_bf16 v[64:67], v[176:179], v[244:247], v[64:67]
	s_setprio 0
	s_barrier
	s_add_i32 s82, s85, s10
	v_lshl_add_u64 v[180:181], v[180:181], 0, s[58:59]
	s_mov_b32 m0, s82
	ds_read_b128 v[188:191], v151 offset:49152
	ds_read_b128 v[220:223], v151 offset:50176
	ds_read_b128 v[224:227], v151 offset:51200
	ds_read_b128 v[228:231], v151 offset:52224
	ds_read_b128 v[232:235], v151 offset:53248
	ds_read_b128 v[236:239], v151 offset:54272
	ds_read_b128 v[240:243], v151 offset:55296
	ds_read_b128 v[244:247], v151 offset:56320
	global_load_lds_dwordx4 v[180:181], off
	s_add_i32 m0, s82, 0x2000
	s_add_u32 s80, s80, 0x40080
	v_lshl_add_u64 v[180:181], v[192:193], 0, s[58:59]
	s_addc_u32 s81, s81, 0
	s_add_i32 s82, s86, s10
	global_load_lds_dwordx4 v[180:181], off
	v_lshl_add_u64 v[180:181], s[80:81], 0, v[98:99]
	s_mov_b32 m0, s82
	s_nop 0
	global_load_lds_dwordx4 v[180:181], off
	v_lshl_add_u64 v[180:181], s[80:81], 0, v[134:135]
	s_add_i32 m0, s82, 0x2000
	s_nop 0
	global_load_lds_dwordx4 v[180:181], off
	v_lshl_add_u64 v[180:181], v[248:249], 0, s[58:59]
	s_mov_b32 m0, s33
	s_nop 0
	global_load_lds_dwordx4 v[180:181], off
	v_lshl_add_u64 v[180:181], v[250:251], 0, s[58:59]
	s_mov_b32 m0, s43
	s_nop 0
	global_load_lds_dwordx4 v[180:181], off
	s_waitcnt vmcnt(8)
	s_waitcnt lgkmcnt(0)
	s_barrier
	s_setprio 1
	s_waitcnt lgkmcnt(0)
	v_mfma_f32_16x16x32_bf16 v[60:63], v[140:143], v[188:191], v[60:63]
	v_mfma_f32_16x16x32_bf16 v[52:55], v[156:159], v[188:191], v[52:55]
	v_mfma_f32_16x16x32_bf16 v[44:47], v[140:143], v[224:227], v[44:47]
	v_mfma_f32_16x16x32_bf16 v[36:39], v[156:159], v[224:227], v[36:39]
	v_mfma_f32_16x16x32_bf16 v[28:31], v[140:143], v[232:235], v[28:31]
	v_mfma_f32_16x16x32_bf16 v[20:23], v[156:159], v[232:235], v[20:23]
	v_mfma_f32_16x16x32_bf16 v[12:15], v[140:143], v[240:243], v[12:15]
	v_mfma_f32_16x16x32_bf16 v[4:7], v[156:159], v[240:243], v[4:7]
	v_mfma_f32_16x16x32_bf16 v[60:63], v[152:155], v[220:223], v[60:63]
	v_mfma_f32_16x16x32_bf16 v[52:55], v[160:163], v[220:223], v[52:55]
	v_mfma_f32_16x16x32_bf16 v[44:47], v[152:155], v[228:231], v[44:47]
	v_mfma_f32_16x16x32_bf16 v[36:39], v[160:163], v[228:231], v[36:39]
	v_mfma_f32_16x16x32_bf16 v[28:31], v[152:155], v[236:239], v[28:31]
	v_mfma_f32_16x16x32_bf16 v[20:23], v[160:163], v[236:239], v[20:23]
	v_mfma_f32_16x16x32_bf16 v[12:15], v[152:155], v[244:247], v[12:15]
	v_mfma_f32_16x16x32_bf16 v[4:7], v[160:163], v[244:247], v[4:7]
	s_setprio 0
	s_setprio 1
	v_mfma_f32_16x16x32_bf16 v[56:59], v[164:167], v[188:191], v[56:59]
	v_mfma_f32_16x16x32_bf16 v[48:51], v[172:175], v[188:191], v[48:51]
	v_mfma_f32_16x16x32_bf16 v[40:43], v[164:167], v[224:227], v[40:43]
	v_mfma_f32_16x16x32_bf16 v[32:35], v[172:175], v[224:227], v[32:35]
	v_mfma_f32_16x16x32_bf16 v[24:27], v[164:167], v[232:235], v[24:27]
	v_mfma_f32_16x16x32_bf16 v[16:19], v[172:175], v[232:235], v[16:19]
	v_mfma_f32_16x16x32_bf16 v[8:11], v[164:167], v[240:243], v[8:11]
	v_mfma_f32_16x16x32_bf16 v[0:3], v[172:175], v[240:243], v[0:3]
	v_mfma_f32_16x16x32_bf16 v[56:59], v[168:171], v[220:223], v[56:59]
	v_mfma_f32_16x16x32_bf16 v[48:51], v[176:179], v[220:223], v[48:51]
	v_mfma_f32_16x16x32_bf16 v[40:43], v[168:171], v[228:231], v[40:43]
	v_mfma_f32_16x16x32_bf16 v[32:35], v[176:179], v[228:231], v[32:35]
	v_mfma_f32_16x16x32_bf16 v[24:27], v[168:171], v[236:239], v[24:27]
	v_mfma_f32_16x16x32_bf16 v[16:19], v[176:179], v[236:239], v[16:19]
	v_mfma_f32_16x16x32_bf16 v[8:11], v[168:171], v[244:247], v[8:11]
	v_mfma_f32_16x16x32_bf16 v[0:3], v[176:179], v[244:247], v[0:3]
	s_setprio 0
	s_barrier
	s_add_i32 s84, s84, 2
	s_add_u32 s78, s78, 0x100
	s_addc_u32 s79, s79, 0
	s_add_u32 s69, s69, 0x100
	s_addc_u32 s71, s71, 0
	s_cmp_gt_u32 s84, 13
	s_cbranch_scc0 .LBB0_346
	s_and_b64 vcc, exec, s[66:67]
	s_cbranch_vccz .LBB0_349
	s_barrier
